# P4 epilogue: x (read once) and table loads nt; with barrier edits + P2 plain stores
# speedup vs baseline: 1.0044x; 1.0005x over previous
; __device__ __forceinline__ unsigned cvt_pk(float lo, float hi) { f32x2_t v = {lo, hi}; bf16x2_t b = __builtin_convertvector(v, bf16x2_t); return __builtin_bit_cast(unsigned, b); }
; #define EO_LOADG(bj) do { _Pragma("unroll") for (int n = 0; n < 2; ++n) { const int c_ = u.pn * 256 + (bj) * 128 + cl + 4 * n; g1a[bj][n] = *(const f32x4*)(g1t + b * D + c_); G2a[bj][n] = *(const f32x4*)(G2t + b * D + c_); } } while (0)
;     __device__ __forceinline__ void operator()(AccRef acc, const pg8::Unit& u, int wr, int wc, int fr_, int fq_) const {
;     ...
;         const int gpm = pm0 + u.pm, b = batch_of_tile(gpm), grow0 = gpm * 256 + wr * 64 + fr, cl = wc * 32 + 8 * fq;
;         const char* xb = (const char*)(gpm * 256 < NPR ? xp + (size_t)gpm * 256 * D : xs + ((size_t)gpm * 256 - NPR) * D) + (size_t)u.pn * 1024;
;         char* x1b = (char*)(x1 + (size_t)u.pm * 256 * D) + (size_t)u.pn * 512;
;         char* xgb = (char*)(xg2 + ((size_t)(u.pm * 16 + u.pn * 4 + (wc >> 1)) << 14));
;         const unsigned loff = (unsigned)(((wr * 64 + fr) * D + cl) * 4), xgl = (unsigned)(((wr * 64 + fr) * 64 + (wc & 1) * 32 + 8 * fq) * 2);
;         float ss[2][4];
; #pragma unroll
;         for (int ai = 0; ai < 2; ++ai)
; #pragma unroll
;             for (int m = 0; m < 4; ++m) ss[ai][m] = 0.f;
;         f32x4 xv[2][2][2], g1a[2][2], G2a[2][2];
;     ...
;         EO_LOADG(0); EO_LOADB(0);
; #pragma unroll
;         for (int k = 0; k < 8; ++k) {
;             const int bj = k >> 2, ai = (k >> 1) & 1;
;             if (k + 1 < 8) EO_LOADB(k + 1);
;             if (k == 3) EO_LOADG(1);
;             asm volatile("" ::: "memory");
; #pragma unroll
;             for (int mm = 0; mm < 2; ++mm) { const int m = 2 * (k & 1) + mm;
;                 const f32x4 v0 = xv[k & 1][mm][0] + g1a[bj][0] * acc[ai][bj][m][0], v1 = xv[k & 1][mm][1] + g1a[bj][1] * acc[ai][bj][m][1];
;                 ss[ai][m] += ((v0[0] * v0[0] + v0[1] * v0[1]) + (v0[2] * v0[2] + v0[3] * v0[3])) + ((v1[0] * v1[0] + v1[1] * v1[1]) + (v1[2] * v1[2] + v1[3] * v1[3]));
;                 const f32x4 h0 = v0 * G2a[bj][0], h1 = v1 * G2a[bj][1]; v4u w; w.x = cvt_pk(h0[0], h0[1]); w.y = cvt_pk(h0[2], h0[3]); w.z = cvt_pk(h1[0], h1[1]); w.w = cvt_pk(h1[2], h1[3]);
;                 *(v4u*)(xgb + (size_t)((2 * bj) << 15) + (size_t)((ai * 128 + m * 16) * 128) + xgl) = w;
.LBB0_451:
	s_sub_i32 s23, s46, 64
	s_lshr_b32 s23, s23, 5
	s_lshr_b32 s9, s46, 3
	s_add_i32 s23, s23, 8
	s_and_b64 s[50:51], s[50:51], exec
	s_cselect_b32 s9, s9, s23
	s_ashr_i32 s31, s30, 31
	s_lshl_b64 s[50:51], s[30:31], 10
	s_lshl_b32 s23, s65, 4
	s_lshl_b32 s31, s30, 2
	s_add_i32 s23, s23, s31
	s_or_b32 s52, s23, s55
	s_ashr_i32 s53, s52, 31
	v_lshlrev_b32_e32 v164, 3, v177
	s_lshl_b64 s[52:53], s[52:53], 15
	v_add_u32_e32 v140, s54, v164
	s_add_u32 s48, s48, s50
	s_addc_u32 s49, s49, s51
	v_lshl_add_u32 v162, s30, 8, v140
	s_lshl_b32 s30, s9, 10
	s_ashr_i32 s31, s30, 31
	v_add_u32_e32 v178, s43, v130
	s_lshl_b64 s[50:51], s[30:31], 2
	v_lshlrev_b32_e32 v141, 12, v178
	s_add_u32 s30, s66, s50
	s_addc_u32 s31, s67, s51
	v_ashrrev_i32_e32 v163, 31, v162
	v_lshl_add_u32 v154, v140, 2, v141
	v_readlane_b32 s68, v250, 36
	v_lshlrev_b64 v[138:139], 2, v[162:163]
	v_lshl_add_u64 v[160:161], s[48:49], 0, v[154:155]
	v_readlane_b32 s69, v250, 37
	s_add_u32 s50, s68, s50
	v_lshl_add_u64 v[134:135], s[30:31], 0, v[138:139]
	v_add_co_u32_e32 v168, vcc, s40, v160
	s_mov_b64 s[74:75], 0x10000
	s_addc_u32 s51, s69, s51
	global_load_dwordx4 v[130:133], v[134:135], off offset:16 nt
	s_nop 0
	global_load_dwordx4 v[134:137], v[134:135], off nt
	s_nop 0
	global_load_dwordx4 v[180:183], v154, s[48:49] offset:16 nt
	global_load_dwordx4 v[184:187], v154, s[48:49] nt
	v_addc_co_u32_e32 v169, vcc, 0, v161, vcc
	v_lshl_add_u64 v[140:141], v[160:161], 0, s[74:75]
	v_lshl_add_u64 v[138:139], s[50:51], 0, v[138:139]
	global_load_dwordx4 v[188:191], v[168:169], off nt
	global_load_dwordx4 v[192:195], v[140:141], off offset:16 nt
	global_load_dwordx4 v[142:145], v[138:139], off nt
	s_nop 0
	global_load_dwordx4 v[138:141], v[138:139], off offset:16 nt
	s_mov_b32 s9, 0x20000
	v_add_u32_e32 v163, s56, v164
	v_add_co_u32_e32 v164, vcc, s9, v160
	s_mov_b64 s[74:75], 0x20000
	s_nop 0
	v_addc_co_u32_e32 v165, vcc, 0, v161, vcc
	global_load_dwordx4 v[196:199], v[164:165], off nt
	v_lshl_add_u64 v[166:167], v[160:161], 0, s[74:75]
	global_load_dwordx4 v[200:203], v[166:167], off offset:16 nt
	s_mov_b32 s9, 0x30000
	v_add_co_u32_e32 v166, vcc, s9, v160
	v_lshlrev_b32_e32 v170, 7, v178
	s_mov_b64 s[74:75], 0x30000
	v_addc_co_u32_e32 v167, vcc, 0, v161, vcc
	v_lshl_add_u32 v212, v163, 1, v170
	v_add_u32_e32 v170, 0x80, v162
	v_lshl_add_u64 v[162:163], v[160:161], 0, s[74:75]
	global_load_dwordx4 v[204:207], v[166:167], off nt
	global_load_dwordx4 v[208:211], v[162:163], off offset:16 nt
	s_add_u32 s52, s71, s52
	s_addc_u32 s53, s72, s53
	s_mov_b32 s9, 0x80000
	v_mov_b32_e32 v213, v155
	v_lshl_add_u64 v[162:163], s[52:53], 0, v[212:213]
	s_waitcnt vmcnt(0)
	v_pk_fma_f32 v[124:125], v[124:125], v[132:133], v[182:183]
	v_pk_fma_f32 v[122:123], v[122:123], v[130:131], v[180:181]
	v_pk_fma_f32 v[128:129], v[128:129], v[136:137], v[186:187]
	v_pk_fma_f32 v[126:127], v[126:127], v[134:135], v[184:185]
	v_mul_f32_e32 v184, v123, v123
	v_mul_f32_e32 v185, v125, v125
	v_fmac_f32_e32 v184, v122, v122
	v_pk_fma_f32 v[180:181], v[116:117], v[132:133], v[194:195]
	v_pk_fma_f32 v[182:183], v[114:115], v[130:131], v[192:193]
	v_fmac_f32_e32 v185, v124, v124
	v_pk_mul_f32 v[116:117], v[144:145], v[128:129]
	v_pk_mul_f32 v[114:115], v[142:143], v[126:127]
	v_pk_mul_f32 v[124:125], v[140:141], v[124:125]
	v_pk_mul_f32 v[122:123], v[138:139], v[122:123]
	v_mul_f32_e32 v171, v127, v127
	v_mul_f32_e32 v179, v129, v129
	v_cvt_pk_bf16_f32 v114, v114, v115
	v_cvt_pk_bf16_f32 v115, v116, v117
	v_cvt_pk_bf16_f32 v116, v122, v123
	v_cvt_pk_bf16_f32 v117, v124, v125
	v_pk_fma_f32 v[120:121], v[120:121], v[136:137], v[190:191]
	v_pk_fma_f32 v[118:119], v[118:119], v[134:135], v[188:189]
	v_fmac_f32_e32 v171, v126, v126
	v_fmac_f32_e32 v179, v128, v128
	global_store_dwordx4 v212, v[114:117], s[52:53]
	v_mul_f32_e32 v186, v119, v119
	v_mul_f32_e32 v187, v121, v121
	v_mul_f32_e32 v114, v183, v183
	v_mul_f32_e32 v115, v181, v181
	v_add_f32_e32 v126, v171, v179
	v_add_f32_e32 v127, v184, v185
	v_fmac_f32_e32 v114, v182, v182
	v_fmac_f32_e32 v115, v180, v180
	v_fmac_f32_e32 v186, v118, v118
	v_add_f32_e32 v179, v126, v127
	v_fmac_f32_e32 v187, v120, v120
	v_add_f32_e32 v127, v114, v115
	v_pk_mul_f32 v[116:117], v[144:145], v[120:121]
	v_pk_mul_f32 v[114:115], v[142:143], v[118:119]
	v_pk_mul_f32 v[118:119], v[140:141], v[180:181]
	v_pk_mul_f32 v[120:121], v[138:139], v[182:183]
	v_cvt_pk_bf16_f32 v114, v114, v115
	v_cvt_pk_bf16_f32 v115, v116, v117
	v_cvt_pk_bf16_f32 v116, v120, v121
	v_cvt_pk_bf16_f32 v117, v118, v119
	global_store_dwordx4 v212, v[114:117], s[52:53] offset:2048
	s_mov_b64 s[52:53], 0x80000
	v_add_f32_e32 v126, v186, v187
	v_add_co_u32_e32 v116, vcc, s9, v160
	v_lshl_add_u64 v[114:115], v[160:161], 0, s[52:53]
	s_nop 0
	v_addc_co_u32_e32 v117, vcc, 0, v161, vcc
	global_load_dwordx4 v[118:121], v[116:117], off nt
	global_load_dwordx4 v[122:125], v[114:115], off offset:16 nt
	s_mov_b32 s9, 0x90000
	s_mov_b64 s[52:53], 0x90000
	v_add_co_u32_e32 v114, vcc, s9, v160
	v_lshl_add_u64 v[180:181], v[160:161], 0, s[52:53]
	s_nop 0
	v_addc_co_u32_e32 v115, vcc, 0, v161, vcc
	v_add_f32_e32 v212, v126, v127
	global_load_dwordx4 v[126:129], v[114:115], off nt
	s_nop 0
	global_load_dwordx4 v[180:183], v[180:181], off offset:16 nt
	v_pk_fma_f32 v[112:113], v[112:113], v[136:137], v[198:199]
	v_pk_fma_f32 v[110:111], v[110:111], v[134:135], v[196:197]
	v_pk_fma_f32 v[184:185], v[106:107], v[130:131], v[200:201]
	v_mul_f32_e32 v106, v111, v111
	v_mul_f32_e32 v107, v113, v113
	v_pk_fma_f32 v[108:109], v[108:109], v[132:133], v[202:203]
	v_fmac_f32_e32 v106, v110, v110
	v_fmac_f32_e32 v107, v112, v112
; __device__ __forceinline__ unsigned cvt_pk(float lo, float hi) { f32x2_t v = {lo, hi}; bf16x2_t b = __builtin_convertvector(v, bf16x2_t); return __builtin_bit_cast(unsigned, b); }
; #define EO_LOADG(bj) do { _Pragma("unroll") for (int n = 0; n < 2; ++n) { const int c_ = u.pn * 256 + (bj) * 128 + cl + 4 * n; g1a[bj][n] = *(const f32x4*)(g1t + b * D + c_); G2a[bj][n] = *(const f32x4*)(G2t + b * D + c_); } } while (0)
; #define EO_LOADB(k) do { _Pragma("unroll") for (int mm = 0; mm < 2; ++mm) { const char* xr = xb + (size_t)(((((k) >> 1) & 1) * 128 + (2 * ((k) & 1) + mm) * 16) * D + ((k) >> 2) * 128) * 4; \
;             xv[(k) & 1][mm][0] = *(const f32x4*)(xr + loff); xv[(k) & 1][mm][1] = *(const f32x4*)(xr + 16 + loff); } } while (0)
;     __device__ __forceinline__ void operator()(AccRef acc, const pg8::Unit& u, int wr, int wc, int fr_, int fq_) const {
;     ...
;         EO_LOADG(0); EO_LOADB(0);
; #pragma unroll
;         for (int k = 0; k < 8; ++k) {
;             const int bj = k >> 2, ai = (k >> 1) & 1;
;             if (k + 1 < 8) EO_LOADB(k + 1);
;             if (k == 3) EO_LOADG(1);
;             asm volatile("" ::: "memory");
; #pragma unroll
;             for (int mm = 0; mm < 2; ++mm) { const int m = 2 * (k & 1) + mm;
;                 const f32x4 v0 = xv[k & 1][mm][0] + g1a[bj][0] * acc[ai][bj][m][0], v1 = xv[k & 1][mm][1] + g1a[bj][1] * acc[ai][bj][m][1];
;                 ss[ai][m] += ((v0[0] * v0[0] + v0[1] * v0[1]) + (v0[2] * v0[2] + v0[3] * v0[3])) + ((v1[0] * v1[0] + v1[1] * v1[1]) + (v1[2] * v1[2] + v1[3] * v1[3]));
;                 const f32x4 h0 = v0 * G2a[bj][0], h1 = v1 * G2a[bj][1]; v4u w; w.x = cvt_pk(h0[0], h0[1]); w.y = cvt_pk(h0[2], h0[3]); w.z = cvt_pk(h1[0], h1[1]); w.w = cvt_pk(h1[2], h1[3]);
;                 *(v4u*)(xgb + (size_t)((2 * bj) << 15) + (size_t)((ai * 128 + m * 16) * 128) + xgl) = w;
;             }
	v_add_f32_e32 v106, v106, v107
	v_mul_f32_e32 v107, v185, v185
	v_mul_f32_e32 v171, v109, v109
	v_pk_mul_f32 v[112:113], v[144:145], v[112:113]
	s_movk_i32 s9, 0x1000
	v_fmac_f32_e32 v107, v184, v184
	v_fmac_f32_e32 v171, v108, v108
	v_pk_mul_f32 v[110:111], v[142:143], v[110:111]
	v_pk_mul_f32 v[186:187], v[140:141], v[108:109]
	v_pk_mul_f32 v[184:185], v[138:139], v[184:185]
	v_cvt_pk_bf16_f32 v109, v112, v113
	v_add_co_u32_e32 v112, vcc, s9, v162
	v_add_f32_e32 v107, v107, v171
	v_cvt_pk_bf16_f32 v108, v110, v111
	v_cvt_pk_bf16_f32 v110, v184, v185
	v_cvt_pk_bf16_f32 v111, v186, v187
	v_addc_co_u32_e32 v113, vcc, 0, v163, vcc
	v_pk_fma_f32 v[104:105], v[104:105], v[136:137], v[206:207]
	v_pk_fma_f32 v[102:103], v[102:103], v[134:135], v[204:205]
	v_add_f32_e32 v106, v106, v107
	global_store_dwordx4 v[112:113], v[108:111], off
	v_mul_f32_e32 v107, v103, v103
	v_pk_fma_f32 v[100:101], v[100:101], v[132:133], v[210:211]
	v_mul_f32_e32 v108, v105, v105
	v_pk_fma_f32 v[98:99], v[98:99], v[130:131], v[208:209]
	v_fmac_f32_e32 v107, v102, v102
	v_fmac_f32_e32 v108, v104, v104
	v_add_f32_e32 v107, v107, v108
	v_mul_f32_e32 v108, v99, v99
	v_mul_f32_e32 v109, v101, v101
	v_fmac_f32_e32 v108, v98, v98
	v_fmac_f32_e32 v109, v100, v100
	v_add_f32_e32 v108, v108, v109
	v_add_f32_e32 v107, v107, v108
	v_pk_mul_f32 v[104:105], v[144:145], v[104:105]
	v_pk_mul_f32 v[102:103], v[142:143], v[102:103]
	v_pk_mul_f32 v[108:109], v[140:141], v[100:101]
	v_pk_mul_f32 v[100:101], v[138:139], v[98:99]
	v_cvt_pk_bf16_f32 v98, v102, v103
	v_cvt_pk_bf16_f32 v99, v104, v105
	v_cvt_pk_bf16_f32 v100, v100, v101
	v_cvt_pk_bf16_f32 v101, v108, v109
	s_mov_b32 s9, 0xa0000
	global_store_dwordx4 v[112:113], v[98:101], off offset:2048
	s_mov_b64 s[52:53], 0xa0000
	v_ashrrev_i32_e32 v171, 31, v170
	v_add_co_u32_e32 v100, vcc, s9, v160
	v_lshl_add_u64 v[98:99], v[160:161], 0, s[52:53]
	s_nop 0
	v_addc_co_u32_e32 v101, vcc, 0, v161, vcc
	global_load_dwordx4 v[102:105], v[100:101], off nt
	global_load_dwordx4 v[108:111], v[98:99], off offset:16 nt
	s_mov_b32 s9, 0xb0000
	v_add_co_u32_e32 v98, vcc, s9, v160
	s_mov_b64 s[52:53], 0xb0000
	s_nop 0
	v_addc_co_u32_e32 v99, vcc, 0, v161, vcc
	v_lshl_add_u64 v[112:113], v[160:161], 0, s[52:53]
	global_load_dwordx4 v[184:187], v[98:99], off nt
	global_load_dwordx4 v[188:191], v[112:113], off offset:16 nt
	s_waitcnt vmcnt(9)
	v_pk_fma_f32 v[96:97], v[96:97], v[136:137], v[120:121]
	v_pk_fma_f32 v[94:95], v[94:95], v[134:135], v[118:119]
	s_waitcnt vmcnt(8)
	v_pk_fma_f32 v[192:193], v[90:91], v[130:131], v[122:123]
	v_mul_f32_e32 v90, v95, v95
	v_mul_f32_e32 v91, v97, v97
	v_pk_fma_f32 v[112:113], v[92:93], v[132:133], v[124:125]
	v_fmac_f32_e32 v90, v94, v94
	v_fmac_f32_e32 v91, v96, v96
	v_add_f32_e32 v196, v90, v91
	v_pk_mul_f32 v[92:93], v[144:145], v[96:97]
	v_pk_mul_f32 v[90:91], v[142:143], v[94:95]
	v_pk_mul_f32 v[94:95], v[140:141], v[112:113]
	s_movk_i32 s9, 0x4000
	v_cvt_pk_bf16_f32 v90, v90, v91
	v_cvt_pk_bf16_f32 v91, v92, v93
	v_cvt_pk_bf16_f32 v93, v94, v95
	v_add_co_u32_e32 v94, vcc, s9, v162
	s_movk_i32 s9, 0x5000
	s_nop 0
	v_addc_co_u32_e32 v95, vcc, 0, v163, vcc
	v_pk_mul_f32 v[96:97], v[138:139], v[192:193]
	v_add_co_u32_e32 v194, vcc, s9, v162
	v_cvt_pk_bf16_f32 v92, v96, v97
	s_nop 0
	v_addc_co_u32_e32 v195, vcc, 0, v163, vcc
	s_waitcnt vmcnt(7)
	v_pk_fma_f32 v[88:89], v[88:89], v[136:137], v[128:129]
	v_pk_fma_f32 v[86:87], v[86:87], v[134:135], v[126:127]
	s_waitcnt vmcnt(6)
	v_pk_fma_f32 v[126:127], v[84:85], v[132:133], v[182:183]
	v_pk_fma_f32 v[128:129], v[82:83], v[130:131], v[180:181]
	global_store_dwordx4 v[194:195], v[90:93], off offset:-4096
	v_pk_mul_f32 v[84:85], v[144:145], v[88:89]
	v_pk_mul_f32 v[82:83], v[142:143], v[86:87]
	v_pk_mul_f32 v[90:91], v[140:141], v[126:127]
	v_pk_mul_f32 v[92:93], v[138:139], v[128:129]
	v_cvt_pk_bf16_f32 v82, v82, v83
	v_cvt_pk_bf16_f32 v83, v84, v85
	v_cvt_pk_bf16_f32 v84, v92, v93
	v_cvt_pk_bf16_f32 v85, v90, v91
	global_store_dwordx4 v[94:95], v[82:85], off offset:2048
	v_mul_f32_e32 v197, v193, v193
	global_load_dwordx4 v[118:121], v154, s[48:49] offset:528 nt
	global_load_dwordx4 v[122:125], v154, s[48:49] offset:512 nt
	v_lshlrev_b64 v[82:83], 2, v[170:171]
	v_lshl_add_u64 v[84:85], s[30:31], 0, v[82:83]
	global_load_dwordx4 v[90:93], v[84:85], off offset:16 nt
	global_load_dwordx4 v[94:97], v[84:85], off nt
	v_mul_f32_e32 v84, v113, v113
	v_fmac_f32_e32 v197, v192, v192
	v_fmac_f32_e32 v84, v112, v112
	v_add_f32_e32 v84, v197, v84
	v_add_f32_e32 v154, v196, v84
	v_mul_f32_e32 v84, v87, v87
	v_mul_f32_e32 v85, v89, v89
	v_fmac_f32_e32 v84, v86, v86
	v_fmac_f32_e32 v85, v88, v88
	v_lshl_add_u64 v[86:87], s[50:51], 0, v[82:83]
	v_add_f32_e32 v112, v84, v85
	global_load_dwordx4 v[82:85], v[86:87], off offset:16 nt
	s_nop 0
	global_load_dwordx4 v[86:89], v[86:87], off nt
	v_mul_f32_e32 v113, v129, v129
	v_mul_f32_e32 v127, v127, v127
	v_fmac_f32_e32 v113, v128, v128
	v_fmac_f32_e32 v127, v126, v126
	v_add_f32_e32 v113, v113, v127
	s_mov_b64 s[30:31], 0x10200
	v_add_f32_e32 v180, v112, v113
	v_lshl_add_u64 v[112:113], v[160:161], 0, s[30:31]
	global_load_dwordx4 v[126:129], v[168:169], off offset:512 nt
	s_nop 0
	global_load_dwordx4 v[168:171], v[112:113], off offset:16 nt
	s_waitcnt vmcnt(13)
	v_pk_fma_f32 v[80:81], v[80:81], v[136:137], v[104:105]
	v_pk_fma_f32 v[78:79], v[78:79], v[134:135], v[102:103]
	v_mul_f32_e32 v103, v81, v81
	v_mul_f32_e32 v102, v79, v79
	s_waitcnt vmcnt(12)
; __device__ __forceinline__ unsigned cvt_pk(float lo, float hi) { f32x2_t v = {lo, hi}; bf16x2_t b = __builtin_convertvector(v, bf16x2_t); return __builtin_bit_cast(unsigned, b); }
; #define EO_LOADG(bj) do { _Pragma("unroll") for (int n = 0; n < 2; ++n) { const int c_ = u.pn * 256 + (bj) * 128 + cl + 4 * n; g1a[bj][n] = *(const f32x4*)(g1t + b * D + c_); G2a[bj][n] = *(const f32x4*)(G2t + b * D + c_); } } while (0)
; #define EO_LOADB(k) do { _Pragma("unroll") for (int mm = 0; mm < 2; ++mm) { const char* xr = xb + (size_t)(((((k) >> 1) & 1) * 128 + (2 * ((k) & 1) + mm) * 16) * D + ((k) >> 2) * 128) * 4; \
;             xv[(k) & 1][mm][0] = *(const f32x4*)(xr + loff); xv[(k) & 1][mm][1] = *(const f32x4*)(xr + 16 + loff); } } while (0)
;     __device__ __forceinline__ void operator()(AccRef acc, const pg8::Unit& u, int wr, int wc, int fr_, int fq_) const {
;     ...
;         for (int k = 0; k < 8; ++k) {
;             const int bj = k >> 2, ai = (k >> 1) & 1;
;             if (k + 1 < 8) EO_LOADB(k + 1);
;             if (k == 3) EO_LOADG(1);
;             asm volatile("" ::: "memory");
; #pragma unroll
;             for (int mm = 0; mm < 2; ++mm) { const int m = 2 * (k & 1) + mm;
;                 const f32x4 v0 = xv[k & 1][mm][0] + g1a[bj][0] * acc[ai][bj][m][0], v1 = xv[k & 1][mm][1] + g1a[bj][1] * acc[ai][bj][m][1];
;                 ss[ai][m] += ((v0[0] * v0[0] + v0[1] * v0[1]) + (v0[2] * v0[2] + v0[3] * v0[3])) + ((v1[0] * v1[0] + v1[1] * v1[1]) + (v1[2] * v1[2] + v1[3] * v1[3]));
;                 const f32x4 h0 = v0 * G2a[bj][0], h1 = v1 * G2a[bj][1]; v4u w; w.x = cvt_pk(h0[0], h0[1]); w.y = cvt_pk(h0[2], h0[3]); w.z = cvt_pk(h1[0], h1[1]); w.w = cvt_pk(h1[2], h1[3]);
;                 *(v4u*)(xgb + (size_t)((2 * bj) << 15) + (size_t)((ai * 128 + m * 16) * 128) + xgl) = w;
;             }
	v_pk_fma_f32 v[76:77], v[76:77], v[132:133], v[110:111]
	v_pk_fma_f32 v[74:75], v[74:75], v[130:131], v[108:109]
	v_fmac_f32_e32 v102, v78, v78
	v_fmac_f32_e32 v103, v80, v80
	v_add_f32_e32 v102, v102, v103
	v_mul_f32_e32 v103, v75, v75
	v_mul_f32_e32 v104, v77, v77
	v_fmac_f32_e32 v103, v74, v74
	v_fmac_f32_e32 v104, v76, v76
	v_add_f32_e32 v103, v103, v104
	v_add_f32_e32 v108, v102, v103
	v_pk_mul_f32 v[80:81], v[144:145], v[80:81]
	v_pk_mul_f32 v[78:79], v[142:143], v[78:79]
	v_pk_mul_f32 v[102:103], v[140:141], v[76:77]
	v_pk_mul_f32 v[76:77], v[138:139], v[74:75]
	v_cvt_pk_bf16_f32 v74, v78, v79
	v_cvt_pk_bf16_f32 v75, v80, v81
	v_cvt_pk_bf16_f32 v76, v76, v77
	v_cvt_pk_bf16_f32 v77, v102, v103
	s_waitcnt vmcnt(11)
	v_pk_fma_f32 v[72:73], v[72:73], v[136:137], v[186:187]
	v_pk_fma_f32 v[70:71], v[70:71], v[134:135], v[184:185]
	global_store_dwordx4 v[194:195], v[74:77], off
	v_mul_f32_e32 v78, v71, v71
	v_mul_f32_e32 v79, v73, v73
	s_waitcnt vmcnt(11)
	v_pk_fma_f32 v[74:75], v[64:65], v[132:133], v[190:191]
	v_pk_fma_f32 v[76:77], v[62:63], v[130:131], v[188:189]
	v_fmac_f32_e32 v78, v70, v70
	v_fmac_f32_e32 v79, v72, v72
	v_pk_mul_f32 v[64:65], v[144:145], v[72:73]
	v_pk_mul_f32 v[62:63], v[142:143], v[70:71]
	v_pk_mul_f32 v[70:71], v[140:141], v[74:75]
	v_pk_mul_f32 v[72:73], v[138:139], v[76:77]
	v_cvt_pk_bf16_f32 v62, v62, v63
	v_cvt_pk_bf16_f32 v63, v64, v65
	v_cvt_pk_bf16_f32 v64, v72, v73
	v_cvt_pk_bf16_f32 v65, v70, v71
	global_store_dwordx4 v[194:195], v[62:65], off offset:2048
	global_load_dwordx4 v[62:65], v[164:165], off offset:512 nt
	s_mov_b64 s[30:31], 0x20200
	v_lshl_add_u64 v[70:71], v[160:161], 0, s[30:31]
	global_load_dwordx4 v[70:73], v[70:71], off offset:16 nt
	v_mul_f32_e32 v77, v77, v77
	v_mul_f32_e32 v75, v75, v75
	v_fmac_f32_e32 v77, v76, v76
	v_fmac_f32_e32 v75, v74, v74
	v_add_f32_e32 v78, v78, v79
	v_add_f32_e32 v74, v77, v75
	s_mov_b64 s[30:31], 0x30200
	v_add_f32_e32 v109, v78, v74
	v_lshl_add_u64 v[78:79], v[160:161], 0, s[30:31]
	global_load_dwordx4 v[74:77], v[166:167], off offset:512 nt
	s_nop 0
	global_load_dwordx4 v[78:81], v[78:79], off offset:16 nt
	s_waitcnt vmcnt(11)
	v_pk_fma_f32 v[60:61], v[60:61], v[92:93], v[120:121]
	s_waitcnt vmcnt(10)
	v_pk_fma_f32 v[68:69], v[68:69], v[96:97], v[124:125]
	v_pk_fma_f32 v[66:67], v[66:67], v[94:95], v[122:123]
	v_pk_fma_f32 v[58:59], v[58:59], v[90:91], v[118:119]
	v_mul_f32_e32 v102, v67, v67
	v_mul_f32_e32 v103, v69, v69
	v_fmac_f32_e32 v102, v66, v66
	v_fmac_f32_e32 v103, v68, v68
	v_mul_f32_e32 v111, v59, v59
	v_mul_f32_e32 v112, v61, v61
	v_add_f32_e32 v110, v102, v103
	v_fmac_f32_e32 v111, v58, v58
	v_fmac_f32_e32 v112, v60, v60
	s_waitcnt vmcnt(8)
	v_pk_mul_f32 v[66:67], v[86:87], v[66:67]
	v_pk_mul_f32 v[102:103], v[84:85], v[60:61]
	v_pk_mul_f32 v[60:61], v[82:83], v[58:59]
	v_cvt_pk_bf16_f32 v58, v66, v67
	v_add_co_u32_e32 v66, vcc, s40, v162
	s_mov_b32 s9, 0x11000
	s_nop 0
	v_addc_co_u32_e32 v67, vcc, 0, v163, vcc
	v_pk_mul_f32 v[68:69], v[88:89], v[68:69]
	v_cvt_pk_bf16_f32 v60, v60, v61
	v_cvt_pk_bf16_f32 v61, v102, v103
	v_add_co_u32_e32 v102, vcc, s9, v162
	v_cvt_pk_bf16_f32 v59, v68, v69
	s_nop 0
	v_addc_co_u32_e32 v103, vcc, 0, v163, vcc
	global_store_dwordx4 v[102:103], v[58:61], off offset:-4096
	s_waitcnt vmcnt(7)
	v_pk_fma_f32 v[68:69], v[52:53], v[92:93], v[170:171]
	v_pk_fma_f32 v[104:105], v[50:51], v[90:91], v[168:169]
	v_pk_fma_f32 v[58:59], v[56:57], v[96:97], v[128:129]
	v_pk_fma_f32 v[60:61], v[54:55], v[94:95], v[126:127]
	v_pk_mul_f32 v[52:53], v[88:89], v[58:59]
	v_pk_mul_f32 v[50:51], v[86:87], v[60:61]
	v_pk_mul_f32 v[54:55], v[84:85], v[68:69]
	v_pk_mul_f32 v[56:57], v[82:83], v[104:105]
	v_cvt_pk_bf16_f32 v50, v50, v51
	v_cvt_pk_bf16_f32 v51, v52, v53
	v_cvt_pk_bf16_f32 v52, v56, v57
	v_cvt_pk_bf16_f32 v53, v54, v55
	global_store_dwordx4 v[66:67], v[50:53], off offset:2048
	s_mov_b64 s[30:31], 0x80200
	v_lshl_add_u64 v[54:55], v[160:161], 0, s[30:31]
	global_load_dwordx4 v[50:53], v[116:117], off offset:512 nt
	v_mul_f32_e32 v61, v61, v61
	global_load_dwordx4 v[54:57], v[54:55], off offset:16 nt
	v_mul_f32_e32 v59, v59, v59
	v_fmac_f32_e32 v61, v60, v60
	v_fmac_f32_e32 v59, v58, v58
	v_add_f32_e32 v58, v61, v59
	v_mul_f32_e32 v59, v105, v105
	v_mul_f32_e32 v60, v69, v69
	v_add_f32_e32 v66, v111, v112
	v_fmac_f32_e32 v59, v104, v104
	v_fmac_f32_e32 v60, v68, v68
	v_add_f32_e32 v66, v110, v66
	v_add_f32_e32 v59, v59, v60
	s_mov_b64 s[30:31], 0x90200
	v_add_f32_e32 v110, v179, v66
	v_add_f32_e32 v58, v58, v59
	v_lshl_add_u64 v[66:67], v[160:161], 0, s[30:31]
	v_add_f32_e32 v104, v212, v58
	global_load_dwordx4 v[58:61], v[114:115], off offset:512 nt
	s_nop 0
	global_load_dwordx4 v[66:69], v[66:67], off offset:16 nt
	s_waitcnt vmcnt(9)
	v_pk_fma_f32 v[48:49], v[48:49], v[96:97], v[64:65]
	v_pk_fma_f32 v[46:47], v[46:47], v[94:95], v[62:63]
	v_mul_f32_e32 v63, v49, v49
	v_mul_f32_e32 v62, v47, v47
	s_waitcnt vmcnt(8)
	v_pk_fma_f32 v[44:45], v[44:45], v[92:93], v[72:73]
	v_pk_fma_f32 v[42:43], v[42:43], v[90:91], v[70:71]
	v_fmac_f32_e32 v62, v46, v46
	v_fmac_f32_e32 v63, v48, v48
	v_add_f32_e32 v62, v62, v63
	v_mul_f32_e32 v63, v43, v43
	v_mul_f32_e32 v64, v45, v45
	v_fmac_f32_e32 v63, v42, v42
	v_fmac_f32_e32 v64, v44, v44
	v_add_f32_e32 v63, v63, v64
	v_add_f32_e32 v64, v62, v63
	v_pk_mul_f32 v[48:49], v[88:89], v[48:49]
	v_pk_mul_f32 v[46:47], v[86:87], v[46:47]
	v_pk_mul_f32 v[62:63], v[84:85], v[44:45]
	v_pk_mul_f32 v[44:45], v[82:83], v[42:43]
	v_cvt_pk_bf16_f32 v42, v46, v47
	v_cvt_pk_bf16_f32 v43, v48, v49
	v_cvt_pk_bf16_f32 v44, v44, v45
	v_cvt_pk_bf16_f32 v45, v62, v63
	global_store_dwordx4 v[102:103], v[42:45], off
	s_waitcnt vmcnt(7)
; __device__ __forceinline__ unsigned cvt_pk(float lo, float hi) { f32x2_t v = {lo, hi}; bf16x2_t b = __builtin_convertvector(v, bf16x2_t); return __builtin_bit_cast(unsigned, b); }
; #define EO_LOADG(bj) do { _Pragma("unroll") for (int n = 0; n < 2; ++n) { const int c_ = u.pn * 256 + (bj) * 128 + cl + 4 * n; g1a[bj][n] = *(const f32x4*)(g1t + b * D + c_); G2a[bj][n] = *(const f32x4*)(G2t + b * D + c_); } } while (0)
; #define EO_LOADB(k) do { _Pragma("unroll") for (int mm = 0; mm < 2; ++mm) { const char* xr = xb + (size_t)(((((k) >> 1) & 1) * 128 + (2 * ((k) & 1) + mm) * 16) * D + ((k) >> 2) * 128) * 4; \
;             xv[(k) & 1][mm][0] = *(const f32x4*)(xr + loff); xv[(k) & 1][mm][1] = *(const f32x4*)(xr + 16 + loff); } } while (0)
;     __device__ __forceinline__ void operator()(AccRef acc, const pg8::Unit& u, int wr, int wc, int fr_, int fq_) const {
;     ...
;         for (int k = 0; k < 8; ++k) {
;             const int bj = k >> 2, ai = (k >> 1) & 1;
;             if (k + 1 < 8) EO_LOADB(k + 1);
;             if (k == 3) EO_LOADG(1);
;             asm volatile("" ::: "memory");
; #pragma unroll
;             for (int mm = 0; mm < 2; ++mm) { const int m = 2 * (k & 1) + mm;
;                 const f32x4 v0 = xv[k & 1][mm][0] + g1a[bj][0] * acc[ai][bj][m][0], v1 = xv[k & 1][mm][1] + g1a[bj][1] * acc[ai][bj][m][1];
;                 ss[ai][m] += ((v0[0] * v0[0] + v0[1] * v0[1]) + (v0[2] * v0[2] + v0[3] * v0[3])) + ((v1[0] * v1[0] + v1[1] * v1[1]) + (v1[2] * v1[2] + v1[3] * v1[3]));
;                 const f32x4 h0 = v0 * G2a[bj][0], h1 = v1 * G2a[bj][1]; v4u w; w.x = cvt_pk(h0[0], h0[1]); w.y = cvt_pk(h0[2], h0[3]); w.z = cvt_pk(h1[0], h1[1]); w.w = cvt_pk(h1[2], h1[3]);
;                 *(v4u*)(xgb + (size_t)((2 * bj) << 15) + (size_t)((ai * 128 + m * 16) * 128) + xgl) = w;
;             }
;             asm volatile("" ::: "memory");
;         }
;     ...
; #pragma unroll
;         for (int ai = 0; ai < 2; ++ai)
; #pragma unroll
;             for (int m = 0; m < 4; ++m) ss[ai][m] = red_sum_16_32(ss[ai][m]);
;         if (fq == 0) {
	v_pk_fma_f32 v[46:47], v[36:37], v[92:93], v[80:81]
	v_pk_fma_f32 v[48:49], v[34:35], v[90:91], v[78:79]
	v_pk_fma_f32 v[42:43], v[40:41], v[96:97], v[76:77]
	v_pk_fma_f32 v[44:45], v[38:39], v[94:95], v[74:75]
	v_pk_mul_f32 v[36:37], v[88:89], v[42:43]
	v_pk_mul_f32 v[34:35], v[86:87], v[44:45]
	v_pk_mul_f32 v[38:39], v[84:85], v[46:47]
	v_pk_mul_f32 v[40:41], v[82:83], v[48:49]
	v_cvt_pk_bf16_f32 v34, v34, v35
	v_cvt_pk_bf16_f32 v35, v36, v37
	v_cvt_pk_bf16_f32 v36, v40, v41
	v_cvt_pk_bf16_f32 v37, v38, v39
	global_store_dwordx4 v[102:103], v[34:37], off offset:2048
	global_load_dwordx4 v[34:37], v[100:101], off offset:512 nt
	s_mov_b64 s[30:31], 0xa0200
	v_lshl_add_u64 v[38:39], v[160:161], 0, s[30:31]
	global_load_dwordx4 v[38:41], v[38:39], off offset:16 nt
	v_mul_f32_e32 v45, v45, v45
	v_mul_f32_e32 v43, v43, v43
	v_fmac_f32_e32 v45, v44, v44
	v_fmac_f32_e32 v43, v42, v42
	v_add_f32_e32 v42, v45, v43
	v_mul_f32_e32 v43, v49, v49
	v_mul_f32_e32 v44, v47, v47
	v_fmac_f32_e32 v43, v48, v48
	v_fmac_f32_e32 v44, v46, v46
	v_add_f32_e32 v43, v43, v44
	v_add_f32_e32 v42, v42, v43
	v_lshl_add_u64 v[46:47], v[160:161], 0, s[6:7]
	v_add_f32_e32 v63, v107, v42
	global_load_dwordx4 v[42:45], v[98:99], off offset:512 nt
	s_nop 0
	global_load_dwordx4 v[46:49], v[46:47], off offset:16 nt
	s_mov_b32 s9, 0x14000
	v_add_f32_e32 v62, v106, v64
	s_waitcnt vmcnt(9)
	v_pk_fma_f32 v[32:33], v[32:33], v[96:97], v[52:53]
	v_pk_fma_f32 v[30:31], v[30:31], v[94:95], v[50:51]
	s_waitcnt vmcnt(8)
	v_pk_fma_f32 v[50:51], v[28:29], v[92:93], v[56:57]
	v_pk_fma_f32 v[52:53], v[26:27], v[90:91], v[54:55]
	v_pk_mul_f32 v[28:29], v[88:89], v[32:33]
	v_pk_mul_f32 v[26:27], v[86:87], v[30:31]
	v_pk_mul_f32 v[54:55], v[84:85], v[50:51]
	v_cvt_pk_bf16_f32 v26, v26, v27
	v_cvt_pk_bf16_f32 v27, v28, v29
	v_cvt_pk_bf16_f32 v29, v54, v55
	v_add_co_u32_e32 v54, vcc, s9, v162
	v_pk_mul_f32 v[56:57], v[82:83], v[52:53]
	s_nop 0
	v_addc_co_u32_e32 v55, vcc, 0, v163, vcc
	v_cvt_pk_bf16_f32 v28, v56, v57
	v_add_co_u32_e32 v56, vcc, s59, v162
	s_waitcnt vmcnt(7)
	v_pk_fma_f32 v[24:25], v[24:25], v[96:97], v[60:61]
	v_addc_co_u32_e32 v57, vcc, 0, v163, vcc
	global_store_dwordx4 v[56:57], v[26:29], off offset:-4096
	v_pk_fma_f32 v[22:23], v[22:23], v[94:95], v[58:59]
	v_cmp_eq_u32_e32 vcc, 0, v177
	s_waitcnt vmcnt(7)
	v_pk_fma_f32 v[26:27], v[20:21], v[92:93], v[68:69]
	v_pk_fma_f32 v[28:29], v[18:19], v[90:91], v[66:67]
	v_pk_mul_f32 v[20:21], v[88:89], v[24:25]
	v_pk_mul_f32 v[18:19], v[86:87], v[22:23]
	v_pk_mul_f32 v[58:59], v[84:85], v[26:27]
	v_pk_mul_f32 v[60:61], v[82:83], v[28:29]
	v_cvt_pk_bf16_f32 v18, v18, v19
	v_cvt_pk_bf16_f32 v19, v20, v21
	v_cvt_pk_bf16_f32 v20, v60, v61
	v_cvt_pk_bf16_f32 v21, v58, v59
	global_store_dwordx4 v[54:55], v[18:21], off offset:2048
	s_waitcnt vmcnt(5)
	v_pk_fma_f32 v[16:17], v[16:17], v[96:97], v[36:37]
	v_mul_f32_e32 v18, v23, v23
	v_mul_f32_e32 v19, v25, v25
	v_fmac_f32_e32 v18, v22, v22
	v_fmac_f32_e32 v19, v24, v24
	v_add_f32_e32 v18, v18, v19
	v_mul_f32_e32 v19, v29, v29
	v_mul_f32_e32 v20, v27, v27
	v_fmac_f32_e32 v19, v28, v28
	v_fmac_f32_e32 v20, v26, v26
	v_add_f32_e32 v19, v19, v20
	v_add_f32_e32 v18, v18, v19
	v_add_f32_e32 v20, v180, v18
	v_mul_f32_e32 v18, v31, v31
	v_mul_f32_e32 v19, v33, v33
	v_fmac_f32_e32 v18, v30, v30
	v_fmac_f32_e32 v19, v32, v32
	v_add_f32_e32 v18, v18, v19
	v_mul_f32_e32 v19, v53, v53
	v_mul_f32_e32 v21, v51, v51
	v_fmac_f32_e32 v19, v52, v52
	v_fmac_f32_e32 v21, v50, v50
	v_add_f32_e32 v19, v19, v21
	v_add_f32_e32 v18, v18, v19
	v_pk_fma_f32 v[14:15], v[14:15], v[94:95], v[34:35]
	v_add_f32_e32 v21, v154, v18
	v_mul_f32_e32 v18, v15, v15
	v_mul_f32_e32 v19, v17, v17
	s_waitcnt vmcnt(4)
	v_pk_fma_f32 v[12:13], v[12:13], v[92:93], v[40:41]
	v_pk_fma_f32 v[10:11], v[10:11], v[90:91], v[38:39]
	v_fmac_f32_e32 v18, v14, v14
	v_fmac_f32_e32 v19, v16, v16
	v_add_f32_e32 v18, v18, v19
	v_mul_f32_e32 v19, v11, v11
	v_mul_f32_e32 v22, v13, v13
	v_fmac_f32_e32 v19, v10, v10
	v_fmac_f32_e32 v22, v12, v12
	v_add_f32_e32 v19, v19, v22
	v_add_f32_e32 v18, v18, v19
	v_add_f32_e32 v22, v108, v18
	v_pk_mul_f32 v[16:17], v[88:89], v[16:17]
	v_pk_mul_f32 v[14:15], v[86:87], v[14:15]
	v_pk_mul_f32 v[18:19], v[84:85], v[12:13]
	v_pk_mul_f32 v[12:13], v[82:83], v[10:11]
	v_cvt_pk_bf16_f32 v10, v14, v15
	v_cvt_pk_bf16_f32 v11, v16, v17
	v_cvt_pk_bf16_f32 v12, v12, v13
	v_cvt_pk_bf16_f32 v13, v18, v19
	s_waitcnt vmcnt(3)
	v_pk_fma_f32 v[8:9], v[8:9], v[96:97], v[44:45]
	v_pk_fma_f32 v[6:7], v[6:7], v[94:95], v[42:43]
	global_store_dwordx4 v[56:57], v[10:13], off
	s_waitcnt vmcnt(3)
	v_pk_fma_f32 v[4:5], v[4:5], v[92:93], v[48:49]
	v_pk_fma_f32 v[2:3], v[2:3], v[90:91], v[46:47]
	v_mul_f32_e32 v10, v7, v7
	v_mul_f32_e32 v11, v9, v9
	v_fmac_f32_e32 v10, v6, v6
	v_fmac_f32_e32 v11, v8, v8
	v_add_f32_e32 v10, v10, v11
	v_mul_f32_e32 v11, v3, v3
	v_mul_f32_e32 v12, v5, v5
	v_fmac_f32_e32 v11, v2, v2
	v_fmac_f32_e32 v12, v4, v4
	v_add_f32_e32 v11, v11, v12
	v_add_f32_e32 v10, v10, v11
	v_add_f32_e32 v16, v109, v10
	v_pk_mul_f32 v[8:9], v[88:89], v[8:9]
	v_pk_mul_f32 v[6:7], v[86:87], v[6:7]
	v_pk_mul_f32 v[10:11], v[84:85], v[4:5]
	v_pk_mul_f32 v[4:5], v[82:83], v[2:3]
	v_cvt_pk_bf16_f32 v2, v6, v7
	v_cvt_pk_bf16_f32 v3, v8, v9
	v_cvt_pk_bf16_f32 v4, v4, v5
	v_cvt_pk_bf16_f32 v5, v10, v11
	global_store_dwordx4 v[56:57], v[2:5], off offset:2048
	v_mov_b32_e32 v6, v62
	v_mov_b32_e32 v8, v63
	v_mov_b32_e32 v2, v110
	s_nop 1
	v_permlane16_swap_b32 v110, v2
	v_mov_b32_e32 v4, v104
	v_add_f32_e32 v2, v110, v2
	v_mov_b32_e32 v3, v2
	s_nop 1
	v_permlane32_swap_b32 v2, v3
	s_nop 1
	v_permlane16_swap_b32 v104, v4
	v_mov_b32_e32 v10, v21
	v_add_f32_e32 v4, v104, v4
	v_mov_b32_e32 v5, v4
	s_nop 1
	v_permlane32_swap_b32 v4, v5
	s_nop 1
	v_permlane16_swap_b32 v62, v6
	v_mov_b32_e32 v12, v20
	v_add_f32_e32 v6, v62, v6
	v_mov_b32_e32 v7, v6
	s_nop 1
	v_permlane32_swap_b32 v6, v7
	s_nop 1
	v_permlane16_swap_b32 v63, v8
	v_mov_b32_e32 v14, v22
	v_add_f32_e32 v8, v63, v8
	v_mov_b32_e32 v9, v8
	s_nop 1
	v_permlane32_swap_b32 v8, v9
	s_nop 1
	v_permlane16_swap_b32 v21, v10
	v_mov_b32_e32 v17, v16
	v_add_f32_e32 v10, v21, v10
	v_mov_b32_e32 v11, v10
	s_nop 1
	v_permlane32_swap_b32 v10, v11
	s_nop 1
	v_permlane16_swap_b32 v20, v12
	s_nop 0
	v_add_f32_e32 v12, v20, v12
	v_mov_b32_e32 v13, v12
	s_nop 1
	v_permlane32_swap_b32 v12, v13
	s_nop 1
	v_permlane16_swap_b32 v22, v14
	s_nop 0
	v_add_f32_e32 v14, v22, v14
	v_mov_b32_e32 v15, v14
	s_nop 1
	v_permlane32_swap_b32 v14, v15
	s_nop 1
	v_permlane16_swap_b32 v16, v17
	s_nop 0
	v_add_f32_e32 v16, v16, v17
	v_mov_b32_e32 v17, v16
	s_nop 1
	v_permlane32_swap_b32 v16, v17
	s_and_saveexec_b64 s[30:31], vcc
	s_cbranch_execz .LBB0_453
;     __device__ __forceinline__ void operator()(AccRef acc, const pg8::Unit& u, int wr, int wc, int fr_, int fq_) const {
;     ...
;         if (fq == 0) {
; #pragma unroll
;             for (int ai = 0; ai < 2; ++ai)
; #pragma unroll
;                 for (int m = 0; m < 4; ++m) atomicAdd(rss2 + grow0 + ai * 128 + m * 16, ss[ai][m] * asc);
;         }
	v_lshl_add_u32 v18, s46, 8, v178
	v_ashrrev_i32_e32 v19, 31, v18
	v_add_f32_e32 v4, v4, v5
	v_add_f32_e32 v5, v2, v3
	v_lshl_add_u64 v[2:3], v[18:19], 2, s[20:21]
	v_add_f32_e32 v16, v16, v17
	v_add_f32_e32 v14, v14, v15
	v_add_f32_e32 v12, v12, v13
	v_add_f32_e32 v10, v10, v11
	v_add_f32_e32 v8, v8, v9
	v_add_f32_e32 v6, v6, v7
	global_atomic_add_f32 v[2:3], v5, off
	global_atomic_add_f32 v[2:3], v4, off offset:64
	global_atomic_add_f32 v[2:3], v6, off offset:128
	global_atomic_add_f32 v[2:3], v8, off offset:192
	global_atomic_add_f32 v[2:3], v10, off offset:512
	global_atomic_add_f32 v[2:3], v12, off offset:576
	global_atomic_add_f32 v[2:3], v14, off offset:640
	global_atomic_add_f32 v[2:3], v16, off offset:704
